# the grid barrier after the last layer's PEER phase is skipped (kernel end is the synchronisation point)
# speedup vs baseline: 1.0156x; 1.0021x over previous
; __device__ __forceinline__ char* opaque(char* q) { size_t z = 0; asm volatile("" : "+s"(z)); return q + z; }
; __device__ __forceinline__ void gbar(unsigned* bar, volatile unsigned* st) {
;   asm volatile("s_waitcnt vmcnt(0) lgkmcnt(0)" ::: "memory");
;   __syncthreads();
;   if (threadIdx.x == 0) {
; __global__ void __launch_bounds__(256, 2) fwd_kernel(P p) {
;     ...
;     gbar((unsigned*)(opaque(p.ws) + OFF_BAR), (volatile unsigned*)(smem + 65520));
;       if (STOP == 10) return;
;   }
.LBB0_1052:
	v_readlane_b32 s6, v255, 60
	s_nop 1
	s_cmp_eq_u32 s6, 3
	s_cbranch_scc1 .Lfin_exit
	s_mov_b64 s[6:7], 0
	s_waitcnt vmcnt(0) lgkmcnt(0)
	s_barrier
	s_mov_b64 s[0:1], exec
	v_readlane_b32 s8, v255, 0
	v_readlane_b32 s9, v255, 1
	s_and_b64 s[8:9], s[0:1], s[8:9]
	s_mov_b64 exec, s[8:9]
	s_cbranch_execnz .LBB0_1053
	s_getpc_b64 s[98:99]

; __device__ __forceinline__ char* opaque(char* q) { size_t z = 0; asm volatile("" : "+s"(z)); return q + z; }
; __global__ void __launch_bounds__(256, 2) fwd_kernel(P p) {
;     ...
;     gbar((unsigned*)(opaque(p.ws) + OFF_BAR), (volatile unsigned*)(smem + 65520));
;       if (STOP == 10) return;
;   }
; }
.Lfin_exit:
.LBB0_1103:
	s_endpgm
